# prep LoRA loop: next column group's weight rows prefetched into spare registers during the current group's tail
# speedup vs baseline: 1.0016x; 1.0016x over previous
; __device__ __forceinline__ float sigm(float x) { return __builtin_amdgcn_rcpf(1.0f + __expf(-x)); }
; __device__ void phase_prep(const Ctx& p, int l, LAS unsigned char* lds) {
;     ...
;         for (int ct = 0; ct < 4; ++ct) {
;             const int crow = h * 64 + ct * 16 + fr, c = h * 64 + ct * 16 + 4 * fq;
;             bf16x8 xw[2], xa[2], xg[5], xv;
; #pragma unroll
;             for (int ks = 0; ks < 2; ++ks) { xw[ks] = *(const bf16x8*)(w2T + crow * 64 + ks * 32 + fq * 8); xa[ks] = *(const bf16x8*)(a2T + crow * 64 + ks * 32 + fq * 8); }
; #pragma unroll
;             for (int ks = 0; ks < 5; ++ks) xg[ks] = *(const bf16x8*)(g2T + crow * 160 + ks * 32 + fq * 8);
;             if (l == 1) xv = *(const bf16x8*)(v2T + crow * 32 + fq * 8); else xv = xw[0];
;     ...
;                 float ew[4], kh[4], kr4[4], ag4[4];
; #pragma unroll
;                 for (int e = 0; e < 4; ++e) {
;                     ew[e] = 0.60653066f * sigm(w0a[e] + aW[e]);
;                     const float a = sigm(a0a[e] + aA[e]); ag4[e] = a;
;                     const float kr = kk4[e] * kka[e]; kr4[e] = kr; ss[tt] += kr * kr;
;                     kh[e] = kk4[e] * (1.0f + (a - 1.0f) * kaa[e]);
;                     bon[tt] += rr[e] * kh[e] * rka[e];
;                 }
.LBB0_1144:
	v_or_b32_e32 v112, s76, v139
	v_ashrrev_i32_e32 v113, 31, v112
	v_lshlrev_b64 v[0:1], 10, v[112:113]
	v_lshl_add_u64 v[118:119], s[30:31], 0, v[0:1]
	v_or_b32_e32 v0, 16, v112
	v_ashrrev_i32_e32 v1, 31, v0
	v_or_b32_e32 v108, s76, v167
	v_lshlrev_b64 v[0:1], 10, v[0:1]
	v_ashrrev_i32_e32 v109, 31, v108
	v_mov_b32_e32 v150, 0
	v_lshl_add_u64 v[120:121], s[30:31], 0, v[0:1]
	v_lshlrev_b64 v[116:117], 9, v[112:113]
	v_lshlrev_b64 v[110:111], 9, v[108:109]
	s_mov_b32 s10, 0
	v_mov_b32_e32 v122, v174
	v_mov_b32_e32 v124, v173
	v_mov_b32_e32 v126, v172
	v_mov_b32_e32 v148, v98
	v_mov_b32_e32 v151, v150
	v_mov_b32_e32 v114, v150
	v_mov_b32_e32 v115, v150
	v_lshlrev_b32_e32 v238, 1, v122
	v_mov_b32_e32 v239, 0
	v_lshl_add_u64 v[240:241], v[90:91], 0, v[238:239]
	v_lshl_add_u64 v[238:239], v[92:93], 0, v[238:239]
	global_load_dwordx4 v[196:199], v[240:241], off
	global_load_dwordx4 v[200:203], v[240:241], off offset:64
	global_load_dwordx4 v[204:207], v[238:239], off
	global_load_dwordx4 v[208:211], v[238:239], off offset:64
	v_lshlrev_b32_e32 v240, 1, v124
	v_mov_b32_e32 v241, 0
	v_lshl_add_u64 v[240:241], v[94:95], 0, v[240:241]
	global_load_dwordx4 v[212:215], v[240:241], off
	global_load_dwordx4 v[216:219], v[240:241], off offset:64
	global_load_dwordx4 v[220:223], v[240:241], off offset:128
	global_load_dwordx4 v[224:227], v[240:241], off offset:192
	global_load_dwordx4 v[228:231], v[240:241], off offset:256
	s_and_b64 vcc, exec, s[46:47]
	s_cbranch_vccnz .Lct_pf0
	v_lshlrev_b32_e32 v238, 1, v126
	v_mov_b32_e32 v239, 0
	v_lshl_add_u64 v[238:239], v[96:97], 0, v[238:239]
	global_load_dwordx4 v[232:235], v[238:239], off
.Lct_pf0:
	s_waitcnt vmcnt(0)
	s_branch .LBB0_1146
.LBB0_1145:
	v_add_f32_e32 v16, v16, v32
	v_add_f32_e32 v12, v12, v36
	v_mul_f32_e32 v16, 0xbfb8aa3b, v16
	v_mul_f32_e32 v12, 0xbfb8aa3b, v12
	v_exp_f32_e32 v16, v16
	v_exp_f32_e32 v32, v12
	v_add_f32_e32 v17, v17, v33
	v_add_f32_e32 v13, v13, v37
	v_mul_f32_e32 v17, 0xbfb8aa3b, v17
	v_mul_f32_e32 v13, 0xbfb8aa3b, v13
	v_add_f32_e32 v12, 1.0, v16
	v_add_f32_e32 v16, 1.0, v32
	v_exp_f32_e32 v17, v17
	v_exp_f32_e32 v32, v13
	s_waitcnt lgkmcnt(0)
	v_lshlrev_b32_e32 v20, 16, v26
	v_and_b32_e32 v21, 0xffff0000, v26
	v_lshlrev_b32_e32 v22, 16, v27
	v_and_b32_e32 v23, 0xffff0000, v27
	v_lshlrev_b32_e32 v26, 16, v44
	v_and_b32_e32 v27, 0xffff0000, v44
	v_add_f32_e32 v13, 1.0, v17
	v_add_f32_e32 v17, 1.0, v32
	v_lshlrev_b32_e32 v41, 16, v45
	v_mul_f32_e32 v26, v76, v26
	v_mul_f32_e32 v40, v77, v27
	s_waitcnt vmcnt(5)
	s_cmpk_eq_i32 s10, 0x60
	s_cbranch_scc1 .Lct_pf1
	v_add_u32_e32 v236, 0x400, v122
	v_add_u32_e32 v237, 0xa00, v124
	v_add_u32_e32 v244, 0x200, v126
	v_lshlrev_b32_e32 v238, 1, v236
	v_mov_b32_e32 v239, 0
	v_lshl_add_u64 v[240:241], v[90:91], 0, v[238:239]
	v_lshl_add_u64 v[238:239], v[92:93], 0, v[238:239]
	global_load_dwordx4 v[196:199], v[240:241], off
	global_load_dwordx4 v[200:203], v[240:241], off offset:64
	global_load_dwordx4 v[204:207], v[238:239], off
	global_load_dwordx4 v[208:211], v[238:239], off offset:64
	v_lshlrev_b32_e32 v240, 1, v237
	v_mov_b32_e32 v241, 0
	v_lshl_add_u64 v[240:241], v[94:95], 0, v[240:241]
	global_load_dwordx4 v[212:215], v[240:241], off
	global_load_dwordx4 v[216:219], v[240:241], off offset:64
	global_load_dwordx4 v[220:223], v[240:241], off offset:128
	global_load_dwordx4 v[224:227], v[240:241], off offset:192
	global_load_dwordx4 v[228:231], v[240:241], off offset:256
	s_and_b64 vcc, exec, s[46:47]
	s_cbranch_vccnz .Lct_pf1x
	v_lshlrev_b32_e32 v238, 1, v244
	v_mov_b32_e32 v239, 0
	v_lshl_add_u64 v[238:239], v[96:97], 0, v[238:239]
	global_load_dwordx4 v[232:235], v[238:239], off
; __device__ __forceinline__ float sigm(float x) { return __builtin_amdgcn_rcpf(1.0f + __expf(-x)); }
; __device__ __forceinline__ u32x2 pack4(float a, float b, float c, float d) { u32x2 w; w.x = cvt_pk_bf16(a, b); w.y = cvt_pk_bf16(c, d); return w; }
; __device__ void phase_prep(const Ctx& p, int l, LAS unsigned char* lds) {
;     ...
;             bf16x8 xw[2], xa[2], xg[5], xv;
; #pragma unroll
;             for (int ks = 0; ks < 2; ++ks) { xw[ks] = *(const bf16x8*)(w2T + crow * 64 + ks * 32 + fq * 8); xa[ks] = *(const bf16x8*)(a2T + crow * 64 + ks * 32 + fq * 8); }
; #pragma unroll
;             for (int ks = 0; ks < 5; ++ks) xg[ks] = *(const bf16x8*)(g2T + crow * 160 + ks * 32 + fq * 8);
;             if (l == 1) xv = *(const bf16x8*)(v2T + crow * 32 + fq * 8); else xv = xw[0];
;     ...
;                 for (int e = 0; e < 4; ++e) {
;                     ew[e] = 0.60653066f * sigm(w0a[e] + aW[e]);
;                     const float a = sigm(a0a[e] + aA[e]); ag4[e] = a;
;                     const float kr = kk4[e] * kka[e]; kr4[e] = kr; ss[tt] += kr * kr;
;                     kh[e] = kk4[e] * (1.0f + (a - 1.0f) * kaa[e]);
;                     bon[tt] += rr[e] * kh[e] * rka[e];
;                 }
;                 const size_t o = (size_t)t * 512 + c;
;                 *(u32x2*)(oR + o) = rw;
;                 *(u32x2*)(oV + o) = pack4(vv[0], vv[1], vv[2], vv[3]);
;                 *(u32x2*)(oE + o) = pack4(ew[0], ew[1], ew[2], ew[3]);
;                 *(u32x2*)(oK + o) = pack4(kh[0], kh[1], kh[2], kh[3]);
;                 *(u32x2*)(oG + o) = pack4(aG[0], aG[1], aG[2], aG[3]);
;                 *(LAS u32x2*)(mrow) = pack4(ag4[0], ag4[1], ag4[2], ag4[3]);
;                 *(LAS u32x2*)(mrow + 512) = pack4(kr4[0], kr4[1], kr4[2], kr4[3]);
.Lct_pf1x:
.Lct_pf1:
	v_mov_b32_e32 v52, v0
	v_mov_b32_e32 v53, v72
	v_mov_b32_e32 v27, v72
	v_rcp_f32_e32 v16, v16
	v_rcp_f32_e32 v17, v17
	v_and_b32_e32 v43, 0xffff0000, v45
	v_mul_f32_e32 v42, v78, v41
	v_pk_fma_f32 v[26:27], v[52:53], v[26:27], v[150:151]
	v_mov_b32_e32 v72, v1
	v_mov_b32_e32 v41, v73
	v_mul_f32_e32 v44, v79, v43
	v_pk_fma_f32 v[26:27], v[72:73], v[40:41], v[26:27]
	v_mov_b32_e32 v40, v2
	v_mov_b32_e32 v41, v74
	v_mov_b32_e32 v43, v74
	v_pk_fma_f32 v[26:27], v[40:41], v[42:43], v[26:27]
	v_mov_b32_e32 v74, v3
	v_mov_b32_e32 v45, v75
	v_pk_fma_f32 v[150:151], v[74:75], v[44:45], v[26:27]
	v_pk_add_f32 v[26:27], v[16:17], -1.0 op_sel_hi:[1,0]
	v_add_f32_e32 v14, v14, v38
	v_add_f32_e32 v15, v15, v39
	v_pk_fma_f32 v[4:5], v[4:5], v[26:27], 1.0 op_sel_hi:[1,1,0]
	v_mul_f32_e32 v14, 0xbfb8aa3b, v14
	v_mul_f32_e32 v15, 0xbfb8aa3b, v15
	v_pk_mul_f32 v[8:9], v[8:9], v[20:21]
	v_pk_mul_f32 v[4:5], v[4:5], v[20:21]
	v_exp_f32_e32 v20, v14
	v_exp_f32_e32 v15, v15
	v_add_f32_e32 v18, v18, v34
	v_add_f32_e32 v19, v19, v35
	v_add_f32_e32 v20, 1.0, v20
	v_add_f32_e32 v15, 1.0, v15
	v_rcp_f32_e32 v20, v20
	v_rcp_f32_e32 v21, v15
	v_mul_f32_e32 v18, 0xbfb8aa3b, v18
	v_mul_f32_e32 v19, 0xbfb8aa3b, v19
	v_exp_f32_e32 v18, v18
	v_exp_f32_e32 v19, v19
	v_lshlrev_b32_e32 v51, 16, v24
	v_pk_add_f32 v[32:33], v[20:21], -1.0 op_sel_hi:[1,0]
	v_and_b32_e32 v54, 0xffff0000, v24
	v_mul_f32_e32 v14, v4, v51
	v_pk_fma_f32 v[6:7], v[6:7], v[32:33], 1.0 op_sel_hi:[1,1,0]
	v_mov_b32_e32 v34, v0
	v_mov_b32_e32 v35, v8
	v_mov_b32_e32 v15, v8
	v_lshlrev_b32_e32 v55, 16, v25
	v_mul_f32_e32 v26, v5, v54
	v_pk_mul_f32 v[10:11], v[10:11], v[22:23]
	v_pk_mul_f32 v[6:7], v[6:7], v[22:23]
	v_pk_fma_f32 v[14:15], v[34:35], v[14:15], v[114:115]
	v_mov_b32_e32 v0, v1
	v_mov_b32_e32 v1, v9
	v_mov_b32_e32 v27, v9
	v_and_b32_e32 v56, 0xffff0000, v25
	v_add_f32_e32 v18, 1.0, v18
	v_add_f32_e32 v19, 1.0, v19
	v_mul_f32_e32 v22, v6, v55
	v_pk_fma_f32 v[0:1], v[0:1], v[26:27], v[14:15]
	v_mov_b32_e32 v14, v2
	v_mov_b32_e32 v15, v10
	v_mov_b32_e32 v23, v10
	v_rcp_f32_e32 v12, v12
	v_rcp_f32_e32 v13, v13
	v_rcp_f32_e32 v18, v18
	v_rcp_f32_e32 v19, v19
	v_mul_f32_e32 v32, v7, v56
	v_pk_fma_f32 v[0:1], v[14:15], v[22:23], v[0:1]
	v_mov_b32_e32 v2, v3
	v_mov_b32_e32 v3, v11
	v_mov_b32_e32 v33, v11
	v_pk_fma_f32 v[114:115], v[2:3], v[32:33], v[0:1]
	v_lshl_add_u64 v[0:1], v[110:111], 0, v[148:149]
	v_lshlrev_b64 v[0:1], 1, v[0:1]
	v_lshl_add_u64 v[2:3], s[6:7], 0, v[0:1]
	v_pk_mul_f32 v[12:13], v[12:13], s[28:29] op_sel_hi:[1,0]
	v_pk_mul_f32 v[18:19], v[18:19], s[28:29] op_sel_hi:[1,0]
	global_store_dwordx2 v[2:3], v[24:25], off
	v_cvt_pk_bf16_f32 v2, v28, v29
	v_cvt_pk_bf16_f32 v3, v30, v31
	v_lshl_add_u64 v[14:15], s[42:43], 0, v[0:1]
	global_store_dwordx2 v[14:15], v[2:3], off
	v_cvt_pk_bf16_f32 v2, v12, v13
	v_cvt_pk_bf16_f32 v3, v18, v19
	v_lshl_add_u64 v[12:13], s[12:13], 0, v[0:1]
	global_store_dwordx2 v[12:13], v[2:3], off
	v_cvt_pk_bf16_f32 v2, v4, v5
	v_cvt_pk_bf16_f32 v3, v6, v7
	v_lshl_add_u64 v[4:5], s[20:21], 0, v[0:1]
	global_store_dwordx2 v[4:5], v[2:3], off
	v_cvt_pk_bf16_f32 v2, v46, v47
	v_cvt_pk_bf16_f32 v3, v48, v49
	v_lshl_add_u64 v[0:1], s[26:27], 0, v[0:1]
	s_add_i32 s10, s10, 32
	global_store_dwordx2 v[0:1], v[2:3], off
	v_cvt_pk_bf16_f32 v0, v16, v17
	v_cvt_pk_bf16_f32 v1, v20, v21
	v_cvt_pk_bf16_f32 v2, v8, v9
	v_cvt_pk_bf16_f32 v3, v10, v11
	v_add_u32_e32 v148, 16, v148
	v_add_u32_e32 v126, 0x200, v126
	v_add_u32_e32 v124, 0xa00, v124
	s_cmpk_eq_i32 s10, 0x80
	v_add_u32_e32 v122, 0x400, v122
	ds_write2st64_b64 v50, v[0:1], v[2:3] offset0:114 offset1:116
	s_cbranch_scc1 .LBB0_1159
.LBB0_1146:
	s_waitcnt vmcnt(5)
	v_mov_b64_e32 v[40:41], v[196:197]
	v_mov_b64_e32 v[42:43], v[198:199]
	v_mov_b64_e32 v[32:33], v[200:201]
	v_mov_b64_e32 v[34:35], v[202:203]
	v_mov_b64_e32 v[36:37], v[204:205]
	v_mov_b64_e32 v[38:39], v[206:207]
	v_mov_b64_e32 v[24:25], v[208:209]
	v_mov_b64_e32 v[26:27], v[210:211]
	v_mov_b64_e32 v[64:65], v[212:213]
	v_mov_b64_e32 v[66:67], v[214:215]
	v_mov_b64_e32 v[60:61], v[216:217]
	v_mov_b64_e32 v[62:63], v[218:219]
	v_mov_b64_e32 v[56:57], v[220:221]
	v_mov_b64_e32 v[58:59], v[222:223]
	v_mov_b64_e32 v[52:53], v[224:225]
	v_mov_b64_e32 v[54:55], v[226:227]
	v_mov_b64_e32 v[48:49], v[228:229]
	v_mov_b64_e32 v[50:51], v[230:231]
	s_and_b64 vcc, exec, s[46:47]
	s_cbranch_vccnz .LBB0_1148
	v_mov_b64_e32 v[28:29], v[232:233]
	v_mov_b64_e32 v[30:31], v[234:235]

; __device__ void phase_prep(const Ctx& p, int l, LAS unsigned char* lds) {
;     ...
;                 f32x4 aW = (f32x4){0.f, 0.f, 0.f, 0.f}, aA = aW, aG = aW, aV = aW;
; #pragma unroll
;                 for (int ks = 0; ks < 2; ++ks) { aW = __builtin_amdgcn_mfma_f32_16x16x32_bf16(xw[ks], *(const LAS bf16x8*)(yrow + 1536 + ks * 32), aW, 0, 0, 0);
;                                                  aA = __builtin_amdgcn_mfma_f32_16x16x32_bf16(xa[ks], *(const LAS bf16x8*)(yrow + 1600 + ks * 32), aA, 0, 0, 0); }
; #pragma unroll
;                 for (int ks = 0; ks < 5; ++ks) aG = __builtin_amdgcn_mfma_f32_16x16x32_bf16(xg[ks], *(const LAS bf16x8*)(yrow + 1664 + ks * 32), aG, 0, 0, 0);
;                 if (l == 1) aV = __builtin_amdgcn_mfma_f32_16x16x32_bf16(xv, *(const LAS bf16x8*)(MID + (tt * 16 + fr) * MIDS + fq * 8), aV, 0, 0, 0);
.LBB0_1151:
	ds_read_b128 v[44:47], v166 offset:3328
	ds_read_b128 v[68:71], v166 offset:3392
	v_mov_b32_e32 v80, 0
	s_and_b64 vcc, s[34:35], exec
	v_mov_b32_e32 v81, 0
	s_waitcnt lgkmcnt(1)
	v_mfma_f32_16x16x32_bf16 v[44:47], v[64:67], v[44:47], 0
	v_mov_b32_e32 v82, 0
	v_mov_b32_e32 v83, 0
	s_waitcnt lgkmcnt(0)
	v_mfma_f32_16x16x32_bf16 v[44:47], v[60:63], v[68:71], v[44:47]
	ds_read_b128 v[68:71], v166 offset:3456
	ds_read_b128 v[72:75], v166 offset:3520
	s_waitcnt lgkmcnt(1)
	v_mfma_f32_16x16x32_bf16 v[44:47], v[56:59], v[68:71], v[44:47]
	ds_read_b128 v[68:71], v166 offset:3584
	s_waitcnt lgkmcnt(1)
	v_mfma_f32_16x16x32_bf16 v[44:47], v[52:55], v[72:75], v[44:47]
	s_waitcnt lgkmcnt(0)
	v_mfma_f32_16x16x32_bf16 v[68:71], v[48:51], v[68:71], v[44:47]
	s_nop 5
	ds_read_b128 v[44:47], v166 offset:3072
	ds_read_b128 v[72:75], v166 offset:3136
	ds_read_b128 v[76:79], v166 offset:3200
	ds_read_b128 v[154:157], v166 offset:3264
	s_waitcnt lgkmcnt(3)
	v_mfma_f32_16x16x32_bf16 v[44:47], v[40:43], v[44:47], 0
	s_waitcnt lgkmcnt(1)
	v_mfma_f32_16x16x32_bf16 v[178:181], v[36:39], v[76:79], 0
	v_mfma_f32_16x16x32_bf16 v[76:79], v[32:35], v[72:75], v[44:47]
	s_waitcnt lgkmcnt(0)
	v_mfma_f32_16x16x32_bf16 v[72:75], v[24:27], v[154:157], v[178:181]
	s_cbranch_vccz .LBB0_1153
	s_nop 1
	ds_read_b128 v[44:47], v176
	s_waitcnt lgkmcnt(0)
	v_mfma_f32_16x16x32_bf16 v[80:83], v[28:31], v[44:47], 0
